# v23_l1
# speedup vs baseline: 1.0043x; 1.0018x over previous
; #define LAS __attribute__((address_space(3)))
; __device__ __forceinline__ void phase_filter(const Params& p, int l, LAS unsigned char* lds, int bid, int G, int tid) {
;     ...
;             for (int e = 0; e < 33; ++e) {
;                 float z;
;                 if (e == 0) z = tt; else { const int bi = (e - 1) & 15; const float fr = 1e-4f + (float)bi * ((15.0f - 1e-4f) / 15.0f); const float rv = fr * wrev, fx = rv - floorf(rv); z = (e <= 16) ? __builtin_amdgcn_cosf(fx) : -__builtin_amdgcn_sinf(fx); }
; #pragma unroll
;                 for (int j4 = 0; j4 < 16; ++j4) { const f32x4 wv = *(const LAS f32x4*)(WL + e * 64 + j4 * 4);
;                     acc[4 * j4] += z * wv[0]; acc[4 * j4 + 1] += z * wv[1]; acc[4 * j4 + 2] += z * wv[2]; acc[4 * j4 + 3] += z * wv[3]; }
;             }
.LBB0_434:
	s_and_b32 s7, s5, 15
	v_cvt_f32_ubyte0_e32 v18, s7
	v_fmamk_f32 v18, v18, 0x3f7fff90, v216
	v_mul_f32_e32 v19, v1, v18
	v_floor_f32_e32 v19, v19
	v_fma_f32 v18, v1, v18, -v19
	s_add_i32 s8, s5, -15
	v_cos_f32_e32 v19, v18
	v_sin_f32_e64 v18, -v18
	s_cmp_lt_u32 s8, 17
	s_cselect_b64 vcc, -1, 0
	s_add_i32 s7, s6, 0
	s_add_i32 s18, s7, 0x20100
	v_cndmask_b32_e32 v92, v18, v19, vcc
	v_mov_b32_e32 v236, s18
	ds_read_b128 v[220:223], v236
	ds_read_b128 v[224:227], v236 offset:16
	ds_read_b128 v[228:231], v236 offset:32
	ds_read_b128 v[232:235], v236 offset:48
	s_add_i32 s18, s7, 0x20110
	s_waitcnt lgkmcnt(3)
	v_pk_fma_f32 v[16:17], v[220:221], v[92:93], v[16:17] op_sel_hi:[1,0,1]
	v_pk_fma_f32 v[14:15], v[222:223], v[92:93], v[14:15] op_sel_hi:[1,0,1]
	ds_read_b128 v[220:223], v236 offset:64
	s_add_i32 s18, s7, 0x20120
	s_waitcnt lgkmcnt(3)
	v_pk_fma_f32 v[12:13], v[224:225], v[92:93], v[12:13] op_sel_hi:[1,0,1]
	v_pk_fma_f32 v[10:11], v[226:227], v[92:93], v[10:11] op_sel_hi:[1,0,1]
	ds_read_b128 v[224:227], v236 offset:80
	s_add_i32 s18, s7, 0x20130
	s_waitcnt lgkmcnt(3)
	v_pk_fma_f32 v[8:9], v[228:229], v[92:93], v[8:9] op_sel_hi:[1,0,1]
	v_pk_fma_f32 v[6:7], v[230:231], v[92:93], v[6:7] op_sel_hi:[1,0,1]
	ds_read_b128 v[228:231], v236 offset:96
	s_add_i32 s18, s7, 0x20140
	s_waitcnt lgkmcnt(3)
	v_pk_fma_f32 v[4:5], v[232:233], v[92:93], v[4:5] op_sel_hi:[1,0,1]
	v_pk_fma_f32 v[2:3], v[234:235], v[92:93], v[2:3] op_sel_hi:[1,0,1]
	ds_read_b128 v[232:235], v236 offset:112
	s_add_i32 s18, s7, 0x20150
	s_waitcnt lgkmcnt(3)
	v_pk_fma_f32 v[88:89], v[220:221], v[92:93], v[88:89] op_sel_hi:[1,0,1]
	v_pk_fma_f32 v[86:87], v[222:223], v[92:93], v[86:87] op_sel_hi:[1,0,1]
	ds_read_b128 v[220:223], v236 offset:128
	s_add_i32 s18, s7, 0x20160
	s_waitcnt lgkmcnt(3)
	v_pk_fma_f32 v[84:85], v[224:225], v[92:93], v[84:85] op_sel_hi:[1,0,1]
	v_pk_fma_f32 v[82:83], v[226:227], v[92:93], v[82:83] op_sel_hi:[1,0,1]
	ds_read_b128 v[224:227], v236 offset:144
	s_add_i32 s18, s7, 0x20170
	s_waitcnt lgkmcnt(3)
	v_pk_fma_f32 v[80:81], v[228:229], v[92:93], v[80:81] op_sel_hi:[1,0,1]
	v_pk_fma_f32 v[78:79], v[230:231], v[92:93], v[78:79] op_sel_hi:[1,0,1]
	ds_read_b128 v[228:231], v236 offset:160
	s_add_i32 s18, s7, 0x20180
	s_waitcnt lgkmcnt(3)
	v_pk_fma_f32 v[76:77], v[232:233], v[92:93], v[76:77] op_sel_hi:[1,0,1]
	v_pk_fma_f32 v[74:75], v[234:235], v[92:93], v[74:75] op_sel_hi:[1,0,1]
	ds_read_b128 v[232:235], v236 offset:176
	s_add_i32 s18, s7, 0x20190
	s_waitcnt lgkmcnt(3)
	v_pk_fma_f32 v[64:65], v[92:93], v[220:221], v[64:65] op_sel_hi:[0,1,1]
	v_pk_fma_f32 v[62:63], v[92:93], v[222:223], v[62:63] op_sel_hi:[0,1,1]
	ds_read_b128 v[220:223], v236 offset:192
	s_add_i32 s18, s7, 0x201a0
	s_waitcnt lgkmcnt(3)
	v_pk_fma_f32 v[60:61], v[92:93], v[224:225], v[60:61] op_sel_hi:[0,1,1]
	v_pk_fma_f32 v[58:59], v[92:93], v[226:227], v[58:59] op_sel_hi:[0,1,1]
	ds_read_b128 v[224:227], v236 offset:208
	s_add_i32 s18, s7, 0x201b0
	s_waitcnt lgkmcnt(3)
	v_pk_fma_f32 v[56:57], v[92:93], v[228:229], v[56:57] op_sel_hi:[0,1,1]
	v_pk_fma_f32 v[54:55], v[92:93], v[230:231], v[54:55] op_sel_hi:[0,1,1]
	ds_read_b128 v[228:231], v236 offset:224
	s_add_i32 s18, s7, 0x201c0
	s_waitcnt lgkmcnt(3)
	v_pk_fma_f32 v[52:53], v[92:93], v[232:233], v[52:53] op_sel_hi:[0,1,1]
	v_pk_fma_f32 v[50:51], v[92:93], v[234:235], v[50:51] op_sel_hi:[0,1,1]
	ds_read_b128 v[232:235], v236 offset:240
	s_add_i32 s18, s7, 0x201d0
	s_waitcnt lgkmcnt(3)
	v_pk_fma_f32 v[30:31], v[92:93], v[220:221], v[48:49] op_sel_hi:[0,1,1]
	v_pk_fma_f32 v[32:33], v[92:93], v[222:223], v[46:47] op_sel_hi:[0,1,1]
	s_add_i32 s18, s7, 0x201e0
	s_waitcnt lgkmcnt(2)
	v_pk_fma_f32 v[26:27], v[92:93], v[224:225], v[44:45] op_sel_hi:[0,1,1]
	v_pk_fma_f32 v[28:29], v[92:93], v[226:227], v[42:43] op_sel_hi:[0,1,1]
	s_add_i32 s18, s7, 0x201f0
	s_waitcnt lgkmcnt(1)
	v_pk_fma_f32 v[22:23], v[92:93], v[228:229], v[40:41] op_sel_hi:[0,1,1]
	v_pk_fma_f32 v[24:25], v[92:93], v[230:231], v[38:39] op_sel_hi:[0,1,1]
	s_and_b32 s18, s8, 15
	s_cmp_lt_u32 s8, 16
	s_cselect_b64 vcc, -1, 0
	s_add_i32 s8, s7, 0x20200
	s_waitcnt lgkmcnt(0)
	v_pk_fma_f32 v[20:21], v[92:93], v[234:235], v[34:35] op_sel_hi:[0,1,1]
	v_cvt_f32_ubyte0_e32 v34, s18
	v_fmamk_f32 v34, v34, 0x3f7fff90, v216
	v_mul_f32_e32 v35, v1, v34
	v_floor_f32_e32 v35, v35
	v_fma_f32 v34, v1, v34, -v35
	v_cos_f32_e32 v35, v34
	v_sin_f32_e64 v34, -v34
	v_pk_fma_f32 v[18:19], v[92:93], v[232:233], v[36:37] op_sel_hi:[0,1,1]
	s_add_i32 s5, s5, 2
	s_addk_i32 s6, 0x200
	v_cndmask_b32_e32 v34, v34, v35, vcc
	v_mov_b32_e32 v237, s8
	ds_read_b128 v[220:223], v237
	ds_read_b128 v[224:227], v237 offset:16
	ds_read_b128 v[228:231], v237 offset:32
	ds_read_b128 v[232:235], v237 offset:48
	s_add_i32 s8, s7, 0x20210
	s_waitcnt lgkmcnt(3)
	v_pk_fma_f32 v[16:17], v[220:221], v[34:35], v[16:17] op_sel_hi:[1,0,1]
	v_pk_fma_f32 v[14:15], v[222:223], v[34:35], v[14:15] op_sel_hi:[1,0,1]
	ds_read_b128 v[220:223], v237 offset:64
	s_add_i32 s8, s7, 0x20220
	s_waitcnt lgkmcnt(3)
	v_pk_fma_f32 v[12:13], v[224:225], v[34:35], v[12:13] op_sel_hi:[1,0,1]
	v_pk_fma_f32 v[10:11], v[226:227], v[34:35], v[10:11] op_sel_hi:[1,0,1]
	ds_read_b128 v[224:227], v237 offset:80
	s_add_i32 s8, s7, 0x20230
	s_waitcnt lgkmcnt(3)
	v_pk_fma_f32 v[8:9], v[228:229], v[34:35], v[8:9] op_sel_hi:[1,0,1]
	v_pk_fma_f32 v[6:7], v[230:231], v[34:35], v[6:7] op_sel_hi:[1,0,1]
	ds_read_b128 v[228:231], v237 offset:96
	s_add_i32 s8, s7, 0x20240
	s_waitcnt lgkmcnt(3)
	v_pk_fma_f32 v[4:5], v[232:233], v[34:35], v[4:5] op_sel_hi:[1,0,1]
	v_pk_fma_f32 v[2:3], v[234:235], v[34:35], v[2:3] op_sel_hi:[1,0,1]
	ds_read_b128 v[232:235], v237 offset:112
	s_add_i32 s8, s7, 0x20250
	s_waitcnt lgkmcnt(3)
; #define LAS __attribute__((address_space(3)))
; __device__ __forceinline__ float hw_sin(float x) { const float r = x * 0.15915494309189535f; return __builtin_amdgcn_sinf(r - floorf(r)); }
; __device__ __forceinline__ void phase_filter(const Params& p, int l, LAS unsigned char* lds, int bid, int G, int tid) {
;     ...
;             for (int e = 0; e < 33; ++e) {
;                 float z;
;                 if (e == 0) z = tt; else { const int bi = (e - 1) & 15; const float fr = 1e-4f + (float)bi * ((15.0f - 1e-4f) / 15.0f); const float rv = fr * wrev, fx = rv - floorf(rv); z = (e <= 16) ? __builtin_amdgcn_cosf(fx) : -__builtin_amdgcn_sinf(fx); }
; #pragma unroll
;                 for (int j4 = 0; j4 < 16; ++j4) { const f32x4 wv = *(const LAS f32x4*)(WL + e * 64 + j4 * 4);
;                     acc[4 * j4] += z * wv[0]; acc[4 * j4 + 1] += z * wv[1]; acc[4 * j4 + 2] += z * wv[2]; acc[4 * j4 + 3] += z * wv[3]; }
;             }
; #pragma unroll
;             for (int j = 0; j < 64; ++j) H[j * 64 + lane] = hw_sin(f1[j] * (acc[j] + b1[j]));
	v_pk_fma_f32 v[88:89], v[220:221], v[34:35], v[88:89] op_sel_hi:[1,0,1]
	v_pk_fma_f32 v[86:87], v[222:223], v[34:35], v[86:87] op_sel_hi:[1,0,1]
	ds_read_b128 v[220:223], v237 offset:128
	s_add_i32 s8, s7, 0x20260
	s_waitcnt lgkmcnt(3)
	v_pk_fma_f32 v[84:85], v[224:225], v[34:35], v[84:85] op_sel_hi:[1,0,1]
	v_pk_fma_f32 v[82:83], v[226:227], v[34:35], v[82:83] op_sel_hi:[1,0,1]
	ds_read_b128 v[224:227], v237 offset:144
	s_add_i32 s8, s7, 0x20270
	s_waitcnt lgkmcnt(3)
	v_pk_fma_f32 v[80:81], v[228:229], v[34:35], v[80:81] op_sel_hi:[1,0,1]
	v_pk_fma_f32 v[78:79], v[230:231], v[34:35], v[78:79] op_sel_hi:[1,0,1]
	ds_read_b128 v[228:231], v237 offset:160
	s_add_i32 s8, s7, 0x20280
	s_waitcnt lgkmcnt(3)
	v_pk_fma_f32 v[76:77], v[232:233], v[34:35], v[76:77] op_sel_hi:[1,0,1]
	v_pk_fma_f32 v[74:75], v[234:235], v[34:35], v[74:75] op_sel_hi:[1,0,1]
	ds_read_b128 v[232:235], v237 offset:176
	s_add_i32 s8, s7, 0x20290
	s_waitcnt lgkmcnt(3)
	v_pk_fma_f32 v[64:65], v[34:35], v[220:221], v[64:65] op_sel_hi:[0,1,1]
	v_pk_fma_f32 v[62:63], v[34:35], v[222:223], v[62:63] op_sel_hi:[0,1,1]
	ds_read_b128 v[220:223], v237 offset:192
	s_add_i32 s8, s7, 0x202a0
	s_waitcnt lgkmcnt(3)
	v_pk_fma_f32 v[60:61], v[34:35], v[224:225], v[60:61] op_sel_hi:[0,1,1]
	v_pk_fma_f32 v[58:59], v[34:35], v[226:227], v[58:59] op_sel_hi:[0,1,1]
	ds_read_b128 v[224:227], v237 offset:208
	s_add_i32 s8, s7, 0x202b0
	s_waitcnt lgkmcnt(3)
	v_pk_fma_f32 v[56:57], v[34:35], v[228:229], v[56:57] op_sel_hi:[0,1,1]
	v_pk_fma_f32 v[54:55], v[34:35], v[230:231], v[54:55] op_sel_hi:[0,1,1]
	ds_read_b128 v[228:231], v237 offset:224
	s_add_i32 s8, s7, 0x202c0
	s_waitcnt lgkmcnt(3)
	v_pk_fma_f32 v[52:53], v[34:35], v[232:233], v[52:53] op_sel_hi:[0,1,1]
	v_pk_fma_f32 v[50:51], v[34:35], v[234:235], v[50:51] op_sel_hi:[0,1,1]
	ds_read_b128 v[232:235], v237 offset:240
	s_add_i32 s8, s7, 0x202d0
	s_waitcnt lgkmcnt(3)
	v_pk_fma_f32 v[48:49], v[34:35], v[220:221], v[30:31] op_sel_hi:[0,1,1]
	v_pk_fma_f32 v[46:47], v[34:35], v[222:223], v[32:33] op_sel_hi:[0,1,1]
	s_add_i32 s8, s7, 0x202e0
	s_add_i32 s7, s7, 0x202f0
	s_cmpk_lg_i32 s6, 0x2000
	s_waitcnt lgkmcnt(2)
	v_pk_fma_f32 v[44:45], v[34:35], v[224:225], v[26:27] op_sel_hi:[0,1,1]
	v_pk_fma_f32 v[42:43], v[34:35], v[226:227], v[28:29] op_sel_hi:[0,1,1]
	s_waitcnt lgkmcnt(1)
	v_pk_fma_f32 v[40:41], v[34:35], v[228:229], v[22:23] op_sel_hi:[0,1,1]
	v_pk_fma_f32 v[38:39], v[34:35], v[230:231], v[24:25] op_sel_hi:[0,1,1]
	s_waitcnt lgkmcnt(0)
	v_pk_fma_f32 v[36:37], v[34:35], v[232:233], v[18:19] op_sel_hi:[0,1,1]
	v_pk_fma_f32 v[34:35], v[34:35], v[234:235], v[20:21] op_sel_hi:[0,1,1]
	s_cbranch_scc1 .LBB0_434
	global_load_dwordx4 v[18:21], v0, s[86:87] offset:48
	global_load_dwordx4 v[22:25], v0, s[86:87] offset:32
	global_load_dwordx4 v[26:29], v0, s[86:87] offset:16
	global_load_dwordx4 v[30:33], v0, s[86:87]
	global_load_dwordx4 v[92:95], v0, s[96:97] offset:48
	global_load_dwordx4 v[102:105], v0, s[96:97] offset:32
	global_load_dwordx4 v[106:109], v0, s[96:97] offset:16
	global_load_dwordx4 v[110:113], v0, s[96:97]
	s_mov_b32 s5, 0
	s_waitcnt vmcnt(0)
	v_add_f32_e32 v1, v16, v110
	v_mul_f32_e32 v1, v30, v1
	v_mul_f32_e32 v16, 0.15915494, v1
	v_floor_f32_e32 v16, v16
	v_fma_f32 v1, v1, 0.15915494, -v16
	v_add_f32_e32 v16, v17, v111
	v_mul_f32_e32 v16, v31, v16
	v_mul_f32_e32 v17, 0.15915494, v16
	v_floor_f32_e32 v17, v17
	v_fma_f32 v16, v16, 0.15915494, -v17
	v_sin_f32_e32 v1, v1
	v_sin_f32_e32 v16, v16
	ds_write2st64_b32 v134, v1, v16 offset1:1
	v_add_f32_e32 v1, v14, v112
	v_mul_f32_e32 v1, v32, v1
	v_mul_f32_e32 v14, 0.15915494, v1
	v_floor_f32_e32 v14, v14
	v_fma_f32 v1, v1, 0.15915494, -v14
	v_add_f32_e32 v14, v15, v113
	v_mul_f32_e32 v14, v33, v14
	v_mul_f32_e32 v15, 0.15915494, v14
	v_floor_f32_e32 v15, v15
	v_fma_f32 v14, v14, 0.15915494, -v15
	v_sin_f32_e32 v1, v1
	v_sin_f32_e32 v14, v14
	ds_write2st64_b32 v134, v1, v14 offset0:2 offset1:3
	v_add_f32_e32 v1, v12, v106
	v_mul_f32_e32 v1, v26, v1
	v_mul_f32_e32 v12, 0.15915494, v1
	v_floor_f32_e32 v12, v12
	v_fma_f32 v1, v1, 0.15915494, -v12
	v_add_f32_e32 v12, v13, v107
	v_mul_f32_e32 v12, v27, v12
	v_mul_f32_e32 v13, 0.15915494, v12
	v_floor_f32_e32 v13, v13
	v_fma_f32 v12, v12, 0.15915494, -v13
	v_sin_f32_e32 v1, v1
	v_sin_f32_e32 v12, v12
	ds_write2st64_b32 v134, v1, v12 offset0:4 offset1:5
	v_add_f32_e32 v1, v10, v108
	v_mul_f32_e32 v1, v28, v1
	v_mul_f32_e32 v10, 0.15915494, v1
	v_floor_f32_e32 v10, v10
	v_fma_f32 v1, v1, 0.15915494, -v10
	v_add_f32_e32 v10, v11, v109
	v_mul_f32_e32 v10, v29, v10
	v_mul_f32_e32 v11, 0.15915494, v10
	v_floor_f32_e32 v11, v11
	v_fma_f32 v10, v10, 0.15915494, -v11
	v_sin_f32_e32 v1, v1
	v_sin_f32_e32 v10, v10
	ds_write2st64_b32 v134, v1, v10 offset0:6 offset1:7
	v_add_f32_e32 v1, v8, v102
	v_mul_f32_e32 v1, v22, v1
	v_mul_f32_e32 v8, 0.15915494, v1
	v_floor_f32_e32 v8, v8
	v_fma_f32 v1, v1, 0.15915494, -v8
	v_add_f32_e32 v8, v9, v103
	v_mul_f32_e32 v8, v23, v8
	v_mul_f32_e32 v9, 0.15915494, v8
	v_floor_f32_e32 v9, v9
	v_fma_f32 v8, v8, 0.15915494, -v9
	v_sin_f32_e32 v1, v1
	v_sin_f32_e32 v8, v8
	ds_write2st64_b32 v134, v1, v8 offset0:8 offset1:9
	v_add_f32_e32 v1, v6, v104
	v_mul_f32_e32 v1, v24, v1
	v_mul_f32_e32 v6, 0.15915494, v1
	v_floor_f32_e32 v6, v6
	v_fma_f32 v1, v1, 0.15915494, -v6
	v_add_f32_e32 v6, v7, v105
	v_mul_f32_e32 v6, v25, v6
	v_mul_f32_e32 v7, 0.15915494, v6
	v_floor_f32_e32 v7, v7
	v_fma_f32 v6, v6, 0.15915494, -v7
	v_sin_f32_e32 v1, v1
	v_sin_f32_e32 v6, v6
	ds_write2st64_b32 v134, v1, v6 offset0:10 offset1:11
	v_add_f32_e32 v1, v4, v92
	v_mul_f32_e32 v1, v18, v1
	v_mul_f32_e32 v4, 0.15915494, v1
	v_floor_f32_e32 v4, v4
	v_fma_f32 v1, v1, 0.15915494, -v4
	v_add_f32_e32 v4, v5, v93
	v_mul_f32_e32 v4, v19, v4
	v_mul_f32_e32 v5, 0.15915494, v4
	v_floor_f32_e32 v5, v5
	v_fma_f32 v4, v4, 0.15915494, -v5
	v_sin_f32_e32 v1, v1
	v_sin_f32_e32 v4, v4
	ds_write2st64_b32 v134, v1, v4 offset0:12 offset1:13
	v_add_f32_e32 v1, v2, v94
	v_mul_f32_e32 v1, v20, v1
	v_mul_f32_e32 v2, 0.15915494, v1
	v_floor_f32_e32 v2, v2
	v_fma_f32 v1, v1, 0.15915494, -v2
	v_add_f32_e32 v2, v3, v95
	v_mul_f32_e32 v2, v21, v2
	v_mul_f32_e32 v3, 0.15915494, v2
	v_floor_f32_e32 v3, v3
	v_fma_f32 v2, v2, 0.15915494, -v3
	v_sin_f32_e32 v1, v1
	v_sin_f32_e32 v2, v2
	ds_write2st64_b32 v134, v1, v2 offset0:14 offset1:15
	global_load_dwordx4 v[2:5], v0, s[86:87] offset:112
	global_load_dwordx4 v[6:9], v0, s[86:87] offset:96
	global_load_dwordx4 v[18:21], v0, s[86:87] offset:80
	global_load_dwordx4 v[26:29], v0, s[86:87] offset:64
	global_load_dwordx4 v[10:13], v0, s[96:97] offset:112
	global_load_dwordx4 v[14:17], v0, s[96:97] offset:96
	global_load_dwordx4 v[22:25], v0, s[96:97] offset:80
	global_load_dwordx4 v[30:33], v0, s[96:97] offset:64
	s_waitcnt vmcnt(0)
; __device__ __forceinline__ float hw_sin(float x) { const float r = x * 0.15915494309189535f; return __builtin_amdgcn_sinf(r - floorf(r)); }
; __device__ __forceinline__ void phase_filter(const Params& p, int l, LAS unsigned char* lds, int bid, int G, int tid) {
;     ...
; #pragma unroll
;             for (int j = 0; j < 64; ++j) H[j * 64 + lane] = hw_sin(f1[j] * (acc[j] + b1[j]));
	v_add_f32_e32 v1, v88, v30
	v_mul_f32_e32 v1, v26, v1
	v_mul_f32_e32 v26, 0.15915494, v1
	v_floor_f32_e32 v26, v26
	v_fma_f32 v1, v1, 0.15915494, -v26
	v_add_f32_e32 v26, v89, v31
	v_mul_f32_e32 v26, v27, v26
	v_mul_f32_e32 v27, 0.15915494, v26
	v_floor_f32_e32 v27, v27
	v_fma_f32 v26, v26, 0.15915494, -v27
	v_sin_f32_e32 v1, v1
	v_sin_f32_e32 v26, v26
	ds_write2st64_b32 v134, v1, v26 offset0:16 offset1:17
	v_add_f32_e32 v1, v86, v32
	v_mul_f32_e32 v1, v28, v1
	v_mul_f32_e32 v26, 0.15915494, v1
	v_floor_f32_e32 v26, v26
	v_fma_f32 v1, v1, 0.15915494, -v26
	v_add_f32_e32 v26, v87, v33
	v_mul_f32_e32 v26, v29, v26
	v_mul_f32_e32 v27, 0.15915494, v26
	v_floor_f32_e32 v27, v27
	v_fma_f32 v26, v26, 0.15915494, -v27
	v_sin_f32_e32 v1, v1
	v_sin_f32_e32 v26, v26
	ds_write2st64_b32 v134, v1, v26 offset0:18 offset1:19
	v_add_f32_e32 v1, v84, v22
	v_mul_f32_e32 v1, v18, v1
	v_mul_f32_e32 v18, 0.15915494, v1
	v_floor_f32_e32 v18, v18
	v_fma_f32 v1, v1, 0.15915494, -v18
	v_add_f32_e32 v18, v85, v23
	v_mul_f32_e32 v18, v19, v18
	v_mul_f32_e32 v19, 0.15915494, v18
	v_floor_f32_e32 v19, v19
	v_fma_f32 v18, v18, 0.15915494, -v19
	v_sin_f32_e32 v1, v1
	v_sin_f32_e32 v18, v18
	ds_write2st64_b32 v134, v1, v18 offset0:20 offset1:21
	v_add_f32_e32 v1, v82, v24
	v_mul_f32_e32 v1, v20, v1
	v_mul_f32_e32 v18, 0.15915494, v1
	v_floor_f32_e32 v18, v18
	v_fma_f32 v1, v1, 0.15915494, -v18
	v_add_f32_e32 v18, v83, v25
	v_mul_f32_e32 v18, v21, v18
	v_mul_f32_e32 v19, 0.15915494, v18
	v_floor_f32_e32 v19, v19
	v_fma_f32 v18, v18, 0.15915494, -v19
	v_sin_f32_e32 v1, v1
	v_sin_f32_e32 v18, v18
	ds_write2st64_b32 v134, v1, v18 offset0:22 offset1:23
	v_add_f32_e32 v1, v80, v14
	v_mul_f32_e32 v1, v6, v1
	v_mul_f32_e32 v6, 0.15915494, v1
	v_floor_f32_e32 v6, v6
	v_fma_f32 v1, v1, 0.15915494, -v6
	v_add_f32_e32 v6, v81, v15
	v_mul_f32_e32 v6, v7, v6
	v_mul_f32_e32 v7, 0.15915494, v6
	v_floor_f32_e32 v7, v7
	v_fma_f32 v6, v6, 0.15915494, -v7
	v_sin_f32_e32 v1, v1
	v_sin_f32_e32 v6, v6
	ds_write2st64_b32 v134, v1, v6 offset0:24 offset1:25
	v_add_f32_e32 v1, v78, v16
	v_mul_f32_e32 v1, v8, v1
	v_mul_f32_e32 v6, 0.15915494, v1
	v_floor_f32_e32 v6, v6
	v_fma_f32 v1, v1, 0.15915494, -v6
	v_add_f32_e32 v6, v79, v17
	v_mul_f32_e32 v6, v9, v6
	v_mul_f32_e32 v7, 0.15915494, v6
	v_floor_f32_e32 v7, v7
	v_fma_f32 v6, v6, 0.15915494, -v7
	v_sin_f32_e32 v1, v1
	v_sin_f32_e32 v6, v6
	ds_write2st64_b32 v134, v1, v6 offset0:26 offset1:27
	v_add_f32_e32 v1, v76, v10
	v_mul_f32_e32 v1, v2, v1
	v_mul_f32_e32 v2, 0.15915494, v1
	v_floor_f32_e32 v2, v2
	v_fma_f32 v1, v1, 0.15915494, -v2
	v_add_f32_e32 v2, v77, v11
	v_mul_f32_e32 v2, v3, v2
	v_mul_f32_e32 v3, 0.15915494, v2
	v_floor_f32_e32 v3, v3
	v_fma_f32 v2, v2, 0.15915494, -v3
	v_sin_f32_e32 v1, v1
	v_sin_f32_e32 v2, v2
	ds_write2st64_b32 v134, v1, v2 offset0:28 offset1:29
	v_add_f32_e32 v1, v74, v12
	v_mul_f32_e32 v1, v4, v1
	v_mul_f32_e32 v2, 0.15915494, v1
	v_floor_f32_e32 v2, v2
	v_fma_f32 v1, v1, 0.15915494, -v2
	v_add_f32_e32 v2, v75, v13
	v_mul_f32_e32 v2, v5, v2
	v_mul_f32_e32 v3, 0.15915494, v2
	v_floor_f32_e32 v3, v3
	v_fma_f32 v2, v2, 0.15915494, -v3
	v_sin_f32_e32 v1, v1
	v_sin_f32_e32 v2, v2
	ds_write2st64_b32 v134, v1, v2 offset0:30 offset1:31
	global_load_dwordx4 v[2:5], v0, s[86:87] offset:176
	global_load_dwordx4 v[10:13], v0, s[86:87] offset:160
	global_load_dwordx4 v[18:21], v0, s[86:87] offset:144
	global_load_dwordx4 v[22:25], v0, s[86:87] offset:128
	global_load_dwordx4 v[6:9], v0, s[96:97] offset:176
	global_load_dwordx4 v[14:17], v0, s[96:97] offset:160
	global_load_dwordx4 v[26:29], v0, s[96:97] offset:144
	global_load_dwordx4 v[30:33], v0, s[96:97] offset:128
	s_waitcnt vmcnt(0)
	v_add_f32_e32 v1, v64, v30
	v_mul_f32_e32 v1, v22, v1
	v_mul_f32_e32 v22, 0.15915494, v1
	v_floor_f32_e32 v22, v22
	v_fma_f32 v1, v1, 0.15915494, -v22
	v_add_f32_e32 v22, v65, v31
	v_mul_f32_e32 v22, v23, v22
	v_mul_f32_e32 v23, 0.15915494, v22
	v_floor_f32_e32 v23, v23
	v_fma_f32 v22, v22, 0.15915494, -v23
	v_sin_f32_e32 v1, v1
	v_sin_f32_e32 v22, v22
	ds_write2st64_b32 v134, v1, v22 offset0:32 offset1:33
	v_add_f32_e32 v1, v62, v32
	v_mul_f32_e32 v1, v24, v1
	v_mul_f32_e32 v22, 0.15915494, v1
	v_floor_f32_e32 v22, v22
	v_fma_f32 v1, v1, 0.15915494, -v22
	v_add_f32_e32 v22, v63, v33
	v_mul_f32_e32 v22, v25, v22
	v_mul_f32_e32 v23, 0.15915494, v22
	v_floor_f32_e32 v23, v23
	v_fma_f32 v22, v22, 0.15915494, -v23
	v_sin_f32_e32 v1, v1
	v_sin_f32_e32 v22, v22
	ds_write2st64_b32 v134, v1, v22 offset0:34 offset1:35
	v_add_f32_e32 v1, v60, v26
	v_mul_f32_e32 v1, v18, v1
	v_mul_f32_e32 v18, 0.15915494, v1
	v_floor_f32_e32 v18, v18
	v_fma_f32 v1, v1, 0.15915494, -v18
	v_add_f32_e32 v18, v61, v27
	v_mul_f32_e32 v18, v19, v18
	v_mul_f32_e32 v19, 0.15915494, v18
	v_floor_f32_e32 v19, v19
	v_fma_f32 v18, v18, 0.15915494, -v19
	v_sin_f32_e32 v1, v1
	v_sin_f32_e32 v18, v18
	ds_write2st64_b32 v134, v1, v18 offset0:36 offset1:37
	v_add_f32_e32 v1, v58, v28
	v_mul_f32_e32 v1, v20, v1
	v_mul_f32_e32 v18, 0.15915494, v1
	v_floor_f32_e32 v18, v18
	v_fma_f32 v1, v1, 0.15915494, -v18
	v_add_f32_e32 v18, v59, v29
	v_mul_f32_e32 v18, v21, v18
	v_mul_f32_e32 v19, 0.15915494, v18
	v_floor_f32_e32 v19, v19
	v_fma_f32 v18, v18, 0.15915494, -v19
	v_sin_f32_e32 v1, v1
	v_sin_f32_e32 v18, v18
	ds_write2st64_b32 v134, v1, v18 offset0:38 offset1:39
	v_add_f32_e32 v1, v56, v14
	v_mul_f32_e32 v1, v10, v1
	v_mul_f32_e32 v10, 0.15915494, v1
	v_floor_f32_e32 v10, v10
	v_fma_f32 v1, v1, 0.15915494, -v10
	v_add_f32_e32 v10, v57, v15
	v_mul_f32_e32 v10, v11, v10
	v_mul_f32_e32 v11, 0.15915494, v10
	v_floor_f32_e32 v11, v11
	v_fma_f32 v10, v10, 0.15915494, -v11
	v_sin_f32_e32 v1, v1
; __device__ __forceinline__ float hw_sin(float x) { const float r = x * 0.15915494309189535f; return __builtin_amdgcn_sinf(r - floorf(r)); }
; __device__ __forceinline__ void phase_filter(const Params& p, int l, LAS unsigned char* lds, int bid, int G, int tid) {
;     ...
; #pragma unroll
;             for (int j = 0; j < 64; ++j) H[j * 64 + lane] = hw_sin(f1[j] * (acc[j] + b1[j]));
;         }
;         {
;             f32x16 c00, c01, c10, c11;
; #pragma unroll
;             for (int v = 0; v < 16; ++v) { c00[v] = 0.f; c01[v] = 0.f; c10[v] = 0.f; c11[v] = 0.f; }
	v_sin_f32_e32 v10, v10
	ds_write2st64_b32 v134, v1, v10 offset0:40 offset1:41
	v_add_f32_e32 v1, v54, v16
	v_mul_f32_e32 v1, v12, v1
	v_mul_f32_e32 v10, 0.15915494, v1
	v_floor_f32_e32 v10, v10
	v_fma_f32 v1, v1, 0.15915494, -v10
	v_add_f32_e32 v10, v55, v17
	v_mul_f32_e32 v10, v13, v10
	v_mul_f32_e32 v11, 0.15915494, v10
	v_floor_f32_e32 v11, v11
	v_fma_f32 v10, v10, 0.15915494, -v11
	v_sin_f32_e32 v1, v1
	v_sin_f32_e32 v10, v10
	ds_write2st64_b32 v134, v1, v10 offset0:42 offset1:43
	v_add_f32_e32 v1, v52, v6
	v_mul_f32_e32 v1, v2, v1
	v_mul_f32_e32 v2, 0.15915494, v1
	v_floor_f32_e32 v2, v2
	v_fma_f32 v1, v1, 0.15915494, -v2
	v_add_f32_e32 v2, v53, v7
	v_mul_f32_e32 v2, v3, v2
	v_mul_f32_e32 v3, 0.15915494, v2
	v_floor_f32_e32 v3, v3
	v_fma_f32 v2, v2, 0.15915494, -v3
	v_sin_f32_e32 v1, v1
	v_sin_f32_e32 v2, v2
	ds_write2st64_b32 v134, v1, v2 offset0:44 offset1:45
	v_add_f32_e32 v1, v50, v8
	v_mul_f32_e32 v1, v4, v1
	v_mul_f32_e32 v2, 0.15915494, v1
	v_floor_f32_e32 v2, v2
	v_fma_f32 v1, v1, 0.15915494, -v2
	v_add_f32_e32 v2, v51, v9
	v_mul_f32_e32 v2, v5, v2
	v_mul_f32_e32 v3, 0.15915494, v2
	v_floor_f32_e32 v3, v3
	v_fma_f32 v2, v2, 0.15915494, -v3
	v_sin_f32_e32 v1, v1
	v_sin_f32_e32 v2, v2
	v_mov_b32_e32 v50, 0
	v_mov_b32_e32 v51, v50
	v_mov_b32_e32 v52, v50
	ds_write2st64_b32 v134, v1, v2 offset0:46 offset1:47
	global_load_dwordx4 v[2:5], v0, s[86:87] offset:240
	global_load_dwordx4 v[10:13], v0, s[86:87] offset:224
	global_load_dwordx4 v[18:21], v0, s[86:87] offset:208
	global_load_dwordx4 v[22:25], v0, s[86:87] offset:192
	global_load_dwordx4 v[6:9], v0, s[96:97] offset:240
	global_load_dwordx4 v[14:17], v0, s[96:97] offset:224
	global_load_dwordx4 v[26:29], v0, s[96:97] offset:208
	global_load_dwordx4 v[30:33], v0, s[96:97] offset:192
	v_mov_b32_e32 v53, v50
	v_mov_b32_e32 v54, v50
	v_mov_b32_e32 v55, v50
	v_mov_b32_e32 v56, v50
	v_mov_b32_e32 v57, v50
	v_mov_b32_e32 v58, v50
	v_mov_b32_e32 v59, v50
	v_mov_b32_e32 v60, v50
	v_mov_b32_e32 v61, v50
	v_mov_b32_e32 v62, v50
	v_mov_b32_e32 v63, v50
	v_mov_b32_e32 v64, v50
	v_mov_b32_e32 v65, v50
	s_waitcnt vmcnt(0)
	v_add_f32_e32 v1, v48, v30
	v_mul_f32_e32 v1, v22, v1
	v_mul_f32_e32 v22, 0.15915494, v1
	v_floor_f32_e32 v22, v22
	v_fma_f32 v1, v1, 0.15915494, -v22
	v_add_f32_e32 v22, v49, v31
	v_mul_f32_e32 v22, v23, v22
	v_mul_f32_e32 v23, 0.15915494, v22
	v_floor_f32_e32 v23, v23
	v_fma_f32 v22, v22, 0.15915494, -v23
	v_sin_f32_e32 v1, v1
	v_sin_f32_e32 v22, v22
	v_mov_b32_e32 v48, v50
	v_mov_b32_e32 v49, v50
	v_mov_b32_e32 v30, v50
	ds_write2st64_b32 v134, v1, v22 offset0:48 offset1:49
	v_add_f32_e32 v1, v46, v32
	v_mul_f32_e32 v1, v24, v1
	v_mul_f32_e32 v22, 0.15915494, v1
	v_floor_f32_e32 v22, v22
	v_fma_f32 v1, v1, 0.15915494, -v22
	v_add_f32_e32 v22, v47, v33
	v_mul_f32_e32 v22, v25, v22
	v_mul_f32_e32 v23, 0.15915494, v22
	v_floor_f32_e32 v23, v23
	v_fma_f32 v22, v22, 0.15915494, -v23
	v_sin_f32_e32 v1, v1
	v_sin_f32_e32 v22, v22
	v_mov_b32_e32 v46, v50
	v_mov_b32_e32 v47, v50
	v_mov_b32_e32 v23, v50
	ds_write2st64_b32 v134, v1, v22 offset0:50 offset1:51
	v_add_f32_e32 v1, v44, v26
	v_mul_f32_e32 v1, v18, v1
	v_mul_f32_e32 v18, 0.15915494, v1
	v_floor_f32_e32 v18, v18
	v_fma_f32 v1, v1, 0.15915494, -v18
	v_add_f32_e32 v18, v45, v27
	v_mul_f32_e32 v18, v19, v18
	v_mul_f32_e32 v19, 0.15915494, v18
	v_floor_f32_e32 v19, v19
	v_fma_f32 v18, v18, 0.15915494, -v19
	v_sin_f32_e32 v1, v1
	v_sin_f32_e32 v18, v18
	v_mov_b32_e32 v44, v50
	v_mov_b32_e32 v45, v50
	v_mov_b32_e32 v22, v50
	ds_write2st64_b32 v134, v1, v18 offset0:52 offset1:53
	v_add_f32_e32 v1, v42, v28
	v_mul_f32_e32 v1, v20, v1
	v_mul_f32_e32 v18, 0.15915494, v1
	v_floor_f32_e32 v18, v18
	v_fma_f32 v1, v1, 0.15915494, -v18
	v_add_f32_e32 v18, v43, v29
	v_mul_f32_e32 v18, v21, v18
	v_mul_f32_e32 v19, 0.15915494, v18
	v_floor_f32_e32 v19, v19
	v_fma_f32 v18, v18, 0.15915494, -v19
	v_sin_f32_e32 v1, v1
	v_sin_f32_e32 v18, v18
	v_mov_b32_e32 v42, v50
	v_mov_b32_e32 v43, v50
	v_mov_b32_e32 v19, v50
	ds_write2st64_b32 v134, v1, v18 offset0:54 offset1:55
	v_add_f32_e32 v1, v40, v14
	v_mul_f32_e32 v1, v10, v1
	v_mul_f32_e32 v10, 0.15915494, v1
	v_floor_f32_e32 v10, v10
	v_fma_f32 v1, v1, 0.15915494, -v10
	v_add_f32_e32 v10, v41, v15
	v_mul_f32_e32 v10, v11, v10
	v_mul_f32_e32 v11, 0.15915494, v10
	v_floor_f32_e32 v11, v11
	v_fma_f32 v10, v10, 0.15915494, -v11
	v_sin_f32_e32 v1, v1
	v_sin_f32_e32 v10, v10
	v_mov_b32_e32 v40, v50
	v_mov_b32_e32 v41, v50
	v_mov_b32_e32 v18, v50
	ds_write2st64_b32 v134, v1, v10 offset0:56 offset1:57
	v_add_f32_e32 v1, v38, v16
	v_mul_f32_e32 v1, v12, v1
	v_mul_f32_e32 v10, 0.15915494, v1
	v_floor_f32_e32 v10, v10
	v_fma_f32 v1, v1, 0.15915494, -v10
	v_add_f32_e32 v10, v39, v17
	v_mul_f32_e32 v10, v13, v10
	v_mul_f32_e32 v11, 0.15915494, v10
	v_floor_f32_e32 v11, v11
	v_fma_f32 v10, v10, 0.15915494, -v11
	v_sin_f32_e32 v1, v1
	v_sin_f32_e32 v10, v10
	v_mov_b32_e32 v38, v50
	v_mov_b32_e32 v39, v50
	v_mov_b32_e32 v20, v50
	ds_write2st64_b32 v134, v1, v10 offset0:58 offset1:59
	v_add_f32_e32 v1, v36, v6
	v_mul_f32_e32 v1, v2, v1
	v_mul_f32_e32 v2, 0.15915494, v1
	v_floor_f32_e32 v2, v2
	v_fma_f32 v1, v1, 0.15915494, -v2
	v_add_f32_e32 v2, v37, v7
	v_mul_f32_e32 v2, v3, v2
	v_mul_f32_e32 v3, 0.15915494, v2
	v_floor_f32_e32 v3, v3
	v_fma_f32 v2, v2, 0.15915494, -v3
	v_sin_f32_e32 v1, v1
	v_sin_f32_e32 v2, v2
	v_mov_b32_e32 v36, v50
	v_mov_b32_e32 v37, v50
	v_mov_b32_e32 v21, v50
	ds_write2st64_b32 v134, v1, v2 offset0:60 offset1:61
	v_add_f32_e32 v1, v34, v8
	v_mul_f32_e32 v1, v4, v1
	v_mul_f32_e32 v2, 0.15915494, v1
	v_floor_f32_e32 v2, v2
	v_fma_f32 v1, v1, 0.15915494, -v2
	v_add_f32_e32 v2, v35, v9
	v_mul_f32_e32 v2, v5, v2
	v_mul_f32_e32 v3, 0.15915494, v2
	v_floor_f32_e32 v3, v3
	v_fma_f32 v2, v2, 0.15915494, -v3
	v_sin_f32_e32 v1, v1
	v_sin_f32_e32 v2, v2
	v_mov_b32_e32 v34, v50
	v_mov_b32_e32 v35, v50
	v_mov_b32_e32 v24, v50
	ds_write2st64_b32 v134, v1, v2 offset0:62 offset1:63
	v_mov_b32_e32 v25, v50
	v_mov_b32_e32 v26, v50
	v_mov_b32_e32 v27, v50
	v_mov_b32_e32 v28, v50
	v_mov_b32_e32 v29, v50
	v_mov_b32_e32 v31, v50
	v_mov_b32_e32 v32, v50
	v_mov_b32_e32 v33, v50
	v_mov_b32_e32 v2, v50
	v_mov_b32_e32 v3, v50
	v_mov_b32_e32 v4, v50
	v_mov_b32_e32 v5, v50
	v_mov_b32_e32 v6, v50
	v_mov_b32_e32 v7, v50
	v_mov_b32_e32 v8, v50
	v_mov_b32_e32 v9, v50
	v_mov_b32_e32 v10, v50
	v_mov_b32_e32 v11, v50
	v_mov_b32_e32 v12, v50
	v_mov_b32_e32 v13, v50
	v_mov_b32_e32 v14, v50
	v_mov_b32_e32 v15, v50
	v_mov_b32_e32 v16, v50
	v_mov_b32_e32 v17, v50
